# operand reuse in the chunk's first stage: K-row fragments read once per wave (K K^T tile from the registers of the K S tile), wave 2 keeps its state fragment for the Q S product
# speedup vs baseline: 1.0069x; 1.0027x over previous
; __device__ __forceinline__ void dn_task(const Params& p, int l, int task, char* smem) {
;     ...
;     {
;       const int did = tid >> 2, pp = did >> 2, wh = did & 3, part = tid & 3;
;       const float* xr = (wh == 0) ? (ks + (2 * pp + 1) * 68) : (wh == 1) ? (qs + (2 * pp) * 68) : (qs + (2 * pp + 1) * 68);
;       const float* yr = (wh == 3) ? (ks + (2 * pp + 1) * 68) : (ks + (2 * pp) * 68);
;       float sdot = 0.f;
; #pragma unroll
;       for (int i = 0; i < 16; ++i) sdot += xr[part * 16 + i] * yr[part * 16 + i];
;       sdot = quad_sum(sdot);
;       if (part == 0) dots[did] = sdot;
;     }
.LBB0_207:
	s_waitcnt lgkmcnt(0)
	s_barrier
	v_and_b32_e32 v221, 63, v172
	v_and_b32_e32 v222, 15, v221
	v_lshrrev_b32_e32 v223, 4, v221
	v_mul_u32_u24_e32 v224, 0x110, v222
	v_lshl_add_u32 v224, v223, 6, v224
	v_mul_u32_u24_e32 v225, 0x240, v223
	v_lshl_add_u32 v225, v222, 2, v225
	v_readfirstlane_b32 s60, v172
	s_nop 3
	s_lshr_b32 s60, s60, 6
	v_lshrrev_b32_e32 v244, 3, v172
	v_lshlrev_b32_e32 v244, 2, v244
	v_sub_u32_e32 v248, v167, v244
	s_and_b32 s61, s60, 1
	s_lshl_b32 s61, s61, 6
	v_mul_u32_u24_e32 v244, 0x840, v223
	v_lshl_add_u32 v244, v222, 2, v244
	s_add_i32 s61, s61, 0x11600
	v_add_u32_e32 v244, s61, v244
	ds_read_b32 v10, v244 offset:0
	ds_read_b32 v11, v244 offset:132
	ds_read_b32 v12, v244 offset:264
	ds_read_b32 v13, v244 offset:396
	ds_read_b32 v14, v244 offset:528
	ds_read_b32 v15, v244 offset:660
	ds_read_b32 v16, v244 offset:792
	ds_read_b32 v17, v244 offset:924
	ds_read_b32 v18, v244 offset:1056
	ds_read_b32 v19, v244 offset:1188
	ds_read_b32 v20, v244 offset:1320
	ds_read_b32 v21, v244 offset:1452
	ds_read_b32 v22, v244 offset:1584
	ds_read_b32 v23, v244 offset:1716
	ds_read_b32 v24, v244 offset:1848
	ds_read_b32 v25, v244 offset:1980
	s_lshr_b32 s61, s60, 1
	s_mul_i32 s70, s61, 0x1100
	v_add_u32_e32 v246, s70, v224
	ds_read_b128 v[66:69], v246 offset:8704
	ds_read_b128 v[70:73], v246 offset:8720
	ds_read_b128 v[74:77], v246 offset:8736
	ds_read_b128 v[78:81], v246 offset:8752
	s_cmp_eq_u32 s60, 3
	s_cbranch_scc1 .Ldc_w3
	s_cmp_eq_u32 s60, 1
	s_cbranch_scc1 .Ldc_k1
	s_waitcnt lgkmcnt(0)
	v_mfma_f32_16x16x4_f32 v[62:65], v66, v10, 0
	v_mfma_f32_16x16x4_f32 v[58:61], v66, v66, 0
	v_mfma_f32_16x16x4_f32 v[62:65], v67, v11, v[62:65]
	v_mfma_f32_16x16x4_f32 v[58:61], v67, v67, v[58:61]
	v_mfma_f32_16x16x4_f32 v[62:65], v68, v12, v[62:65]
	v_mfma_f32_16x16x4_f32 v[58:61], v68, v68, v[58:61]
	v_mfma_f32_16x16x4_f32 v[62:65], v69, v13, v[62:65]
	v_mfma_f32_16x16x4_f32 v[58:61], v69, v69, v[58:61]
	v_mfma_f32_16x16x4_f32 v[62:65], v70, v14, v[62:65]
	v_mfma_f32_16x16x4_f32 v[58:61], v70, v70, v[58:61]
	v_mfma_f32_16x16x4_f32 v[62:65], v71, v15, v[62:65]
	v_mfma_f32_16x16x4_f32 v[58:61], v71, v71, v[58:61]
	v_mfma_f32_16x16x4_f32 v[62:65], v72, v16, v[62:65]
	v_mfma_f32_16x16x4_f32 v[58:61], v72, v72, v[58:61]
	v_mfma_f32_16x16x4_f32 v[62:65], v73, v17, v[62:65]
	v_mfma_f32_16x16x4_f32 v[58:61], v73, v73, v[58:61]
	v_mfma_f32_16x16x4_f32 v[62:65], v74, v18, v[62:65]
	v_mfma_f32_16x16x4_f32 v[58:61], v74, v74, v[58:61]
	v_mfma_f32_16x16x4_f32 v[62:65], v75, v19, v[62:65]
	v_mfma_f32_16x16x4_f32 v[58:61], v75, v75, v[58:61]
	v_mfma_f32_16x16x4_f32 v[62:65], v76, v20, v[62:65]
	v_mfma_f32_16x16x4_f32 v[58:61], v76, v76, v[58:61]
	v_mfma_f32_16x16x4_f32 v[62:65], v77, v21, v[62:65]
	v_mfma_f32_16x16x4_f32 v[58:61], v77, v77, v[58:61]
	v_mfma_f32_16x16x4_f32 v[62:65], v78, v22, v[62:65]
	v_mfma_f32_16x16x4_f32 v[58:61], v78, v78, v[58:61]
	v_mfma_f32_16x16x4_f32 v[62:65], v79, v23, v[62:65]
	v_mfma_f32_16x16x4_f32 v[58:61], v79, v79, v[58:61]
	v_mfma_f32_16x16x4_f32 v[62:65], v80, v24, v[62:65]
	v_mfma_f32_16x16x4_f32 v[58:61], v80, v80, v[58:61]
	v_mfma_f32_16x16x4_f32 v[62:65], v81, v25, v[62:65]
	v_mfma_f32_16x16x4_f32 v[58:61], v81, v81, v[58:61]
	s_branch .Ldc_b1
.Ldc_k1:
	v_add_u32_e32 v244, 0x1100, v224
	ds_read_b128 v[26:29], v244 offset:8704
	ds_read_b128 v[30:33], v244 offset:8720
	ds_read_b128 v[34:37], v244 offset:8736
	ds_read_b128 v[38:41], v244 offset:8752
	s_waitcnt lgkmcnt(0)
	v_mfma_f32_16x16x4_f32 v[62:65], v66, v10, 0
	v_mfma_f32_16x16x4_f32 v[58:61], v26, v66, 0
	v_mfma_f32_16x16x4_f32 v[62:65], v67, v11, v[62:65]
	v_mfma_f32_16x16x4_f32 v[58:61], v27, v67, v[58:61]
	v_mfma_f32_16x16x4_f32 v[62:65], v68, v12, v[62:65]
	v_mfma_f32_16x16x4_f32 v[58:61], v28, v68, v[58:61]
	v_mfma_f32_16x16x4_f32 v[62:65], v69, v13, v[62:65]
	v_mfma_f32_16x16x4_f32 v[58:61], v29, v69, v[58:61]
	v_mfma_f32_16x16x4_f32 v[62:65], v70, v14, v[62:65]
	v_mfma_f32_16x16x4_f32 v[58:61], v30, v70, v[58:61]
	v_mfma_f32_16x16x4_f32 v[62:65], v71, v15, v[62:65]
	v_mfma_f32_16x16x4_f32 v[58:61], v31, v71, v[58:61]
	v_mfma_f32_16x16x4_f32 v[62:65], v72, v16, v[62:65]
	v_mfma_f32_16x16x4_f32 v[58:61], v32, v72, v[58:61]
	v_mfma_f32_16x16x4_f32 v[62:65], v73, v17, v[62:65]
	v_mfma_f32_16x16x4_f32 v[58:61], v33, v73, v[58:61]
	v_mfma_f32_16x16x4_f32 v[62:65], v74, v18, v[62:65]
	v_mfma_f32_16x16x4_f32 v[58:61], v34, v74, v[58:61]
	v_mfma_f32_16x16x4_f32 v[62:65], v75, v19, v[62:65]
	v_mfma_f32_16x16x4_f32 v[58:61], v35, v75, v[58:61]
	v_mfma_f32_16x16x4_f32 v[62:65], v76, v20, v[62:65]
	v_mfma_f32_16x16x4_f32 v[58:61], v36, v76, v[58:61]
	v_mfma_f32_16x16x4_f32 v[62:65], v77, v21, v[62:65]
	v_mfma_f32_16x16x4_f32 v[58:61], v37, v77, v[58:61]
	v_mfma_f32_16x16x4_f32 v[62:65], v78, v22, v[62:65]
	v_mfma_f32_16x16x4_f32 v[58:61], v38, v78, v[58:61]
	v_mfma_f32_16x16x4_f32 v[62:65], v79, v23, v[62:65]
	v_mfma_f32_16x16x4_f32 v[58:61], v39, v79, v[58:61]
	v_mfma_f32_16x16x4_f32 v[62:65], v80, v24, v[62:65]
	v_mfma_f32_16x16x4_f32 v[58:61], v40, v80, v[58:61]
	v_mfma_f32_16x16x4_f32 v[62:65], v81, v25, v[62:65]
	v_mfma_f32_16x16x4_f32 v[58:61], v41, v81, v[58:61]
	s_branch .Ldc_b1

.Ldc_s2q:
	s_cmp_eq_u32 s60, 2
	s_cbranch_scc1 .Ldc_q2
	s_and_b32 s61, s60, 1
	s_lshl_b32 s61, s61, 6
	v_mul_u32_u24_e32 v244, 0x840, v223
	v_lshl_add_u32 v244, v222, 2, v244
	s_add_i32 s61, s61, 0x11600
	v_add_u32_e32 v244, s61, v244
	ds_read_b32 v10, v244 offset:0
	ds_read_b32 v11, v244 offset:132
	ds_read_b32 v12, v244 offset:264
	ds_read_b32 v13, v244 offset:396
	ds_read_b32 v14, v244 offset:528
	ds_read_b32 v15, v244 offset:660
	ds_read_b32 v16, v244 offset:792
	ds_read_b32 v17, v244 offset:924
	ds_read_b32 v18, v244 offset:1056
	ds_read_b32 v19, v244 offset:1188
	ds_read_b32 v20, v244 offset:1320
	ds_read_b32 v21, v244 offset:1452
	ds_read_b32 v22, v244 offset:1584
	ds_read_b32 v23, v244 offset:1716
	ds_read_b32 v24, v244 offset:1848
	ds_read_b32 v25, v244 offset:1980
.Ldc_q2:
	ds_read_b128 v[26:29], v224 offset:0
	ds_read_b128 v[30:33], v224 offset:16
	ds_read_b128 v[34:37], v224 offset:32
	ds_read_b128 v[38:41], v224 offset:48
	v_lshlrev_b32_e32 v245, 2, v222
	v_add_u32_e32 v245, 0x13700, v245
	ds_read_b32 v42, v245 offset:0
	s_waitcnt lgkmcnt(0)
	v_mul_f32_e32 v26, v42, v26
	v_mul_f32_e32 v27, v42, v27
	v_mul_f32_e32 v28, v42, v28
	v_mul_f32_e32 v29, v42, v29
	v_mul_f32_e32 v30, v42, v30
	v_mul_f32_e32 v31, v42, v31
	v_mul_f32_e32 v32, v42, v32
	v_mul_f32_e32 v33, v42, v33
	v_mul_f32_e32 v34, v42, v34
	v_mul_f32_e32 v35, v42, v35
	v_mul_f32_e32 v36, v42, v36
	v_mul_f32_e32 v37, v42, v37
	v_mul_f32_e32 v38, v42, v38
	v_mul_f32_e32 v39, v42, v39
	v_mul_f32_e32 v40, v42, v40
	v_mul_f32_e32 v41, v42, v41
	s_nop 1
	v_mfma_f32_16x16x4_f32 v[58:61], v26, v10, 0
	v_mfma_f32_16x16x4_f32 v[58:61], v27, v11, v[58:61]
	v_mfma_f32_16x16x4_f32 v[58:61], v28, v12, v[58:61]
	v_mfma_f32_16x16x4_f32 v[58:61], v29, v13, v[58:61]
	v_mfma_f32_16x16x4_f32 v[58:61], v30, v14, v[58:61]
	v_mfma_f32_16x16x4_f32 v[58:61], v31, v15, v[58:61]
	v_mfma_f32_16x16x4_f32 v[58:61], v32, v16, v[58:61]
	v_mfma_f32_16x16x4_f32 v[58:61], v33, v17, v[58:61]
	v_mfma_f32_16x16x4_f32 v[58:61], v34, v18, v[58:61]
	v_mfma_f32_16x16x4_f32 v[58:61], v35, v19, v[58:61]
	v_mfma_f32_16x16x4_f32 v[58:61], v36, v20, v[58:61]
	v_mfma_f32_16x16x4_f32 v[58:61], v37, v21, v[58:61]
	v_mfma_f32_16x16x4_f32 v[58:61], v38, v22, v[58:61]
	v_mfma_f32_16x16x4_f32 v[58:61], v39, v23, v[58:61]
	v_mfma_f32_16x16x4_f32 v[58:61], v40, v24, v[58:61]
	v_mfma_f32_16x16x4_f32 v[58:61], v41, v25, v[58:61]
	ds_read_b128 v[26:29], v224 offset:4352
	ds_read_b128 v[30:33], v224 offset:4368
	ds_read_b128 v[34:37], v224 offset:4384
	ds_read_b128 v[38:41], v224 offset:4400
	v_lshlrev_b32_e32 v245, 2, v222
	v_add_u32_e32 v245, 0x13700, v245
	ds_read_b32 v42, v245 offset:64
	s_waitcnt lgkmcnt(0)
	v_mul_f32_e32 v26, v42, v26
	v_mul_f32_e32 v27, v42, v27
	v_mul_f32_e32 v28, v42, v28
	v_mul_f32_e32 v29, v42, v29
	v_mul_f32_e32 v30, v42, v30
	v_mul_f32_e32 v31, v42, v31
	v_mul_f32_e32 v32, v42, v32
	v_mul_f32_e32 v33, v42, v33
	v_mul_f32_e32 v34, v42, v34
	v_mul_f32_e32 v35, v42, v35
	v_mul_f32_e32 v36, v42, v36
	v_mul_f32_e32 v37, v42, v37
	v_mul_f32_e32 v38, v42, v38
	v_mul_f32_e32 v39, v42, v39
	v_mul_f32_e32 v40, v42, v40
	v_mul_f32_e32 v41, v42, v41
	s_nop 1
	v_mfma_f32_16x16x4_f32 v[62:65], v26, v10, 0
	v_mfma_f32_16x16x4_f32 v[62:65], v27, v11, v[62:65]
	v_mfma_f32_16x16x4_f32 v[62:65], v28, v12, v[62:65]
	v_mfma_f32_16x16x4_f32 v[62:65], v29, v13, v[62:65]
	v_mfma_f32_16x16x4_f32 v[62:65], v30, v14, v[62:65]
	v_mfma_f32_16x16x4_f32 v[62:65], v31, v15, v[62:65]
	v_mfma_f32_16x16x4_f32 v[62:65], v32, v16, v[62:65]
	v_mfma_f32_16x16x4_f32 v[62:65], v33, v17, v[62:65]
	v_mfma_f32_16x16x4_f32 v[62:65], v34, v18, v[62:65]
	v_mfma_f32_16x16x4_f32 v[62:65], v35, v19, v[62:65]
	v_mfma_f32_16x16x4_f32 v[62:65], v36, v20, v[62:65]
	v_mfma_f32_16x16x4_f32 v[62:65], v37, v21, v[62:65]
	v_mfma_f32_16x16x4_f32 v[62:65], v38, v22, v[62:65]
	v_mfma_f32_16x16x4_f32 v[62:65], v39, v23, v[62:65]
	v_mfma_f32_16x16x4_f32 v[62:65], v40, v24, v[62:65]
	v_mfma_f32_16x16x4_f32 v[62:65], v41, v25, v[62:65]
